# FFN1-up GEMM epilogue: 8 per-row rsqrt loads issued together with counted waits
# baseline (speedup 1.0000x reference)
.LBB0_836:
	v_lshl_add_u32 v150, s22, 8, v1
	v_ashrrev_i32_e32 v151, 31, v150
	v_lshl_add_u64 v[146:147], v[150:151], 2, s[8:9]
	global_load_dword v158, v[146:147], off
	global_load_dword v184, v[146:147], off offset:64
	global_load_dword v185, v[146:147], off offset:128
	global_load_dword v186, v[146:147], off offset:192
	global_load_dword v187, v[146:147], off offset:512
	global_load_dword v188, v[146:147], off offset:576
	global_load_dword v189, v[146:147], off offset:640
	global_load_dword v190, v[146:147], off offset:704
	v_or_b32_e32 v162, 16, v150
	v_ashrrev_i32_e32 v163, 31, v162
	v_lshl_add_u64 v[164:165], v[162:163], 2, s[8:9]
	v_lshl_or_b32 v148, s61, 7, v153
	v_mov_b64_e32 v[146:147], s[64:65]
	v_ashrrev_i32_e32 v149, 31, v148
	v_mad_i64_i32 v[160:161], s[62:63], v150, s60, v[146:147]
	v_lshlrev_b64 v[148:149], 1, v[148:149]
	v_lshl_add_u64 v[160:161], v[160:161], 0, v[148:149]
	s_andn2_b64 vcc, exec, s[0:1]
	s_mov_b64 s[0:1], -1
	s_waitcnt vmcnt(7)
	v_pk_mul_f32 v[128:129], v[128:129], v[158:159] op_sel_hi:[1,0]
	v_pk_mul_f32 v[126:127], v[126:127], v[158:159] op_sel_hi:[1,0]
	v_pk_mul_f32 v[124:125], v[124:125], v[158:159] op_sel_hi:[1,0]
	v_pk_mul_f32 v[122:123], v[122:123], v[158:159] op_sel_hi:[1,0]
	v_pk_mul_f32 v[120:121], v[120:121], v[158:159] op_sel_hi:[1,0]
	v_pk_mul_f32 v[118:119], v[118:119], v[158:159] op_sel_hi:[1,0]
	v_pk_mul_f32 v[116:117], v[116:117], v[158:159] op_sel_hi:[1,0]
	v_pk_mul_f32 v[114:115], v[114:115], v[158:159] op_sel_hi:[1,0]
	v_mul_f32_e32 v151, 0xbfb8aa3b, v126
	v_mul_f32_e32 v157, 0xbfb8aa3b, v127
	v_mul_f32_e32 v158, 0xbfb8aa3b, v128
	v_mul_f32_e32 v159, 0xbfb8aa3b, v129
	v_mul_f32_e32 v163, 0xbfb8aa3b, v122
	v_mul_f32_e32 v166, 0xbfb8aa3b, v123
	v_mul_f32_e32 v167, 0xbfb8aa3b, v124
	v_mul_f32_e32 v168, 0xbfb8aa3b, v125
	v_exp_f32_e32 v151, v151
	v_exp_f32_e32 v157, v157
	v_exp_f32_e32 v158, v158
	v_exp_f32_e32 v159, v159
	v_exp_f32_e32 v163, v163
	v_exp_f32_e32 v166, v166
	v_exp_f32_e32 v167, v167
	v_exp_f32_e32 v168, v168
	v_add_f32_e32 v151, 1.0, v151
	v_add_f32_e32 v157, 1.0, v157
	v_add_f32_e32 v169, 1.0, v158
	v_add_f32_e32 v170, 1.0, v159
	v_add_f32_e32 v163, 1.0, v163
	v_add_f32_e32 v171, 1.0, v166
	v_add_f32_e32 v172, 1.0, v167
	v_add_f32_e32 v173, 1.0, v168
	v_rcp_f32_e32 v158, v151
	v_rcp_f32_e32 v159, v157
	v_rcp_f32_e32 v166, v169
	v_rcp_f32_e32 v167, v170
	v_rcp_f32_e32 v168, v163
	v_rcp_f32_e32 v169, v171
	v_rcp_f32_e32 v170, v172
	v_rcp_f32_e32 v171, v173
	v_pk_mul_f32 v[126:127], v[126:127], v[158:159]
	v_pk_mul_f32 v[128:129], v[128:129], v[166:167]
	v_pk_mul_f32 v[122:123], v[122:123], v[168:169]
	v_pk_mul_f32 v[124:125], v[124:125], v[170:171]
	v_pk_mul_f32 v[118:119], v[118:119], v[126:127]
	v_pk_mul_f32 v[120:121], v[120:121], v[128:129]
	v_pk_mul_f32 v[122:123], v[114:115], v[122:123]
	v_pk_mul_f32 v[124:125], v[116:117], v[124:125]
	v_cvt_pk_bf16_f32 v114, v118, v119
	v_cvt_pk_bf16_f32 v115, v120, v121
	v_cvt_pk_bf16_f32 v116, v122, v123
	v_cvt_pk_bf16_f32 v117, v124, v125
	global_store_dwordx4 v[160:161], v[114:117], off
	s_waitcnt vmcnt(7)
	s_nop 1
	v_mov_b32_e32 v114, v184
	v_mad_i64_i32 v[118:119], s[62:63], v162, s60, v[146:147]
	v_or_b32_e32 v116, 32, v150
	v_ashrrev_i32_e32 v117, 31, v116
	v_lshl_add_u64 v[120:121], v[116:117], 2, s[8:9]
	v_lshl_add_u64 v[118:119], v[118:119], 0, v[148:149]
	v_pk_mul_f32 v[112:113], v[112:113], v[114:115] op_sel_hi:[1,0]
	v_pk_mul_f32 v[110:111], v[110:111], v[114:115] op_sel_hi:[1,0]
	v_pk_mul_f32 v[108:109], v[108:109], v[114:115] op_sel_hi:[1,0]
	v_pk_mul_f32 v[106:107], v[106:107], v[114:115] op_sel_hi:[1,0]
	v_pk_mul_f32 v[104:105], v[104:105], v[114:115] op_sel_hi:[1,0]
	v_pk_mul_f32 v[102:103], v[102:103], v[114:115] op_sel_hi:[1,0]
	v_pk_mul_f32 v[100:101], v[100:101], v[114:115] op_sel_hi:[1,0]
	v_pk_mul_f32 v[98:99], v[98:99], v[114:115] op_sel_hi:[1,0]
	v_mul_f32_e32 v114, 0xbfb8aa3b, v110
	v_mul_f32_e32 v115, 0xbfb8aa3b, v111
	v_mul_f32_e32 v117, 0xbfb8aa3b, v112
	v_mul_f32_e32 v122, 0xbfb8aa3b, v113
	v_mul_f32_e32 v123, 0xbfb8aa3b, v106
	v_mul_f32_e32 v124, 0xbfb8aa3b, v107
	v_mul_f32_e32 v125, 0xbfb8aa3b, v108
	v_mul_f32_e32 v126, 0xbfb8aa3b, v109
	v_exp_f32_e32 v114, v114
	v_exp_f32_e32 v115, v115
	v_exp_f32_e32 v117, v117
	v_exp_f32_e32 v122, v122
	v_exp_f32_e32 v123, v123
	v_exp_f32_e32 v124, v124
	v_exp_f32_e32 v125, v125
	v_exp_f32_e32 v126, v126
	v_add_f32_e32 v114, 1.0, v114
	v_add_f32_e32 v115, 1.0, v115
	v_add_f32_e32 v117, 1.0, v117
	v_add_f32_e32 v127, 1.0, v122
	v_add_f32_e32 v128, 1.0, v123
	v_add_f32_e32 v129, 1.0, v124
	v_add_f32_e32 v151, 1.0, v125
	v_add_f32_e32 v157, 1.0, v126
	v_rcp_f32_e32 v114, v114
	v_rcp_f32_e32 v115, v115
	v_rcp_f32_e32 v122, v117
	v_rcp_f32_e32 v123, v127
	v_rcp_f32_e32 v124, v128
	v_rcp_f32_e32 v125, v129
	v_rcp_f32_e32 v126, v151
	v_rcp_f32_e32 v127, v157
	v_pk_mul_f32 v[110:111], v[110:111], v[114:115]
	v_pk_mul_f32 v[112:113], v[112:113], v[122:123]
	v_pk_mul_f32 v[106:107], v[106:107], v[124:125]
	v_pk_mul_f32 v[108:109], v[108:109], v[126:127]
	v_pk_mul_f32 v[102:103], v[102:103], v[110:111]
	v_pk_mul_f32 v[104:105], v[104:105], v[112:113]
	v_pk_mul_f32 v[106:107], v[98:99], v[106:107]
	v_pk_mul_f32 v[108:109], v[100:101], v[108:109]
	v_cvt_pk_bf16_f32 v98, v102, v103
	v_cvt_pk_bf16_f32 v99, v104, v105
	v_cvt_pk_bf16_f32 v100, v106, v107
	v_cvt_pk_bf16_f32 v101, v108, v109
	global_store_dwordx4 v[118:119], v[98:101], off
	s_waitcnt vmcnt(7)
	s_nop 1
	v_mov_b32_e32 v98, v185
	v_mad_i64_i32 v[102:103], s[62:63], v116, s60, v[146:147]
	v_or_b32_e32 v100, 48, v150
	v_ashrrev_i32_e32 v101, 31, v100
	v_lshl_add_u64 v[104:105], v[100:101], 2, s[8:9]
	v_lshl_add_u64 v[102:103], v[102:103], 0, v[148:149]
	v_pk_mul_f32 v[96:97], v[96:97], v[98:99] op_sel_hi:[1,0]
	v_pk_mul_f32 v[94:95], v[94:95], v[98:99] op_sel_hi:[1,0]
	v_pk_mul_f32 v[92:93], v[92:93], v[98:99] op_sel_hi:[1,0]
	v_pk_mul_f32 v[90:91], v[90:91], v[98:99] op_sel_hi:[1,0]
	v_pk_mul_f32 v[88:89], v[88:89], v[98:99] op_sel_hi:[1,0]
	v_pk_mul_f32 v[86:87], v[86:87], v[98:99] op_sel_hi:[1,0]
	v_pk_mul_f32 v[84:85], v[84:85], v[98:99] op_sel_hi:[1,0]
	v_pk_mul_f32 v[82:83], v[82:83], v[98:99] op_sel_hi:[1,0]
	v_mul_f32_e32 v98, 0xbfb8aa3b, v94
	v_mul_f32_e32 v99, 0xbfb8aa3b, v95
	v_mul_f32_e32 v101, 0xbfb8aa3b, v96
	v_mul_f32_e32 v106, 0xbfb8aa3b, v97
	v_mul_f32_e32 v107, 0xbfb8aa3b, v90
	v_mul_f32_e32 v108, 0xbfb8aa3b, v91
	v_mul_f32_e32 v109, 0xbfb8aa3b, v92
	v_mul_f32_e32 v110, 0xbfb8aa3b, v93
	v_exp_f32_e32 v98, v98
	v_exp_f32_e32 v99, v99
	v_exp_f32_e32 v101, v101
	v_exp_f32_e32 v106, v106
	v_exp_f32_e32 v107, v107
	v_exp_f32_e32 v108, v108
	v_exp_f32_e32 v109, v109
	v_exp_f32_e32 v110, v110
	v_add_f32_e32 v98, 1.0, v98
	v_add_f32_e32 v99, 1.0, v99
	v_add_f32_e32 v101, 1.0, v101
	v_add_f32_e32 v111, 1.0, v106
	v_add_f32_e32 v112, 1.0, v107
	v_add_f32_e32 v113, 1.0, v108
	v_add_f32_e32 v114, 1.0, v109
	v_add_f32_e32 v115, 1.0, v110
	v_rcp_f32_e32 v98, v98
	v_rcp_f32_e32 v99, v99
	v_rcp_f32_e32 v106, v101
	v_rcp_f32_e32 v107, v111
	v_rcp_f32_e32 v108, v112
	v_rcp_f32_e32 v109, v113
	v_rcp_f32_e32 v110, v114
	v_rcp_f32_e32 v111, v115
	v_pk_mul_f32 v[94:95], v[94:95], v[98:99]
	v_pk_mul_f32 v[96:97], v[96:97], v[106:107]
	v_pk_mul_f32 v[90:91], v[90:91], v[108:109]
	v_pk_mul_f32 v[92:93], v[92:93], v[110:111]
	v_pk_mul_f32 v[86:87], v[86:87], v[94:95]
	v_pk_mul_f32 v[88:89], v[88:89], v[96:97]
	v_pk_mul_f32 v[90:91], v[82:83], v[90:91]
	v_pk_mul_f32 v[92:93], v[84:85], v[92:93]
	v_cvt_pk_bf16_f32 v82, v86, v87
	v_cvt_pk_bf16_f32 v83, v88, v89
	v_cvt_pk_bf16_f32 v84, v90, v91
	v_cvt_pk_bf16_f32 v85, v92, v93
	global_store_dwordx4 v[102:103], v[82:85], off
	s_waitcnt vmcnt(7)
	s_nop 1
	v_mov_b32_e32 v82, v186
	v_mad_i64_i32 v[86:87], s[62:63], v100, s60, v[146:147]
	v_add_u32_e32 v84, 0x80, v150
	v_ashrrev_i32_e32 v85, 31, v84
	v_lshl_add_u64 v[88:89], v[84:85], 2, s[8:9]
	v_lshl_add_u64 v[86:87], v[86:87], 0, v[148:149]
	v_pk_mul_f32 v[80:81], v[80:81], v[82:83] op_sel_hi:[1,0]
	v_pk_mul_f32 v[78:79], v[78:79], v[82:83] op_sel_hi:[1,0]
	v_pk_mul_f32 v[76:77], v[76:77], v[82:83] op_sel_hi:[1,0]
	v_pk_mul_f32 v[74:75], v[74:75], v[82:83] op_sel_hi:[1,0]
	v_pk_mul_f32 v[72:73], v[72:73], v[82:83] op_sel_hi:[1,0]
	v_pk_mul_f32 v[70:71], v[70:71], v[82:83] op_sel_hi:[1,0]
	v_pk_mul_f32 v[68:69], v[68:69], v[82:83] op_sel_hi:[1,0]
	v_pk_mul_f32 v[66:67], v[66:67], v[82:83] op_sel_hi:[1,0]
	v_mul_f32_e32 v82, 0xbfb8aa3b, v78
	v_mul_f32_e32 v83, 0xbfb8aa3b, v79
	v_mul_f32_e32 v85, 0xbfb8aa3b, v80
	v_mul_f32_e32 v90, 0xbfb8aa3b, v81
	v_mul_f32_e32 v91, 0xbfb8aa3b, v74
	v_mul_f32_e32 v92, 0xbfb8aa3b, v75
	v_mul_f32_e32 v93, 0xbfb8aa3b, v76
	v_mul_f32_e32 v94, 0xbfb8aa3b, v77
	v_exp_f32_e32 v82, v82
	v_exp_f32_e32 v83, v83
	v_exp_f32_e32 v85, v85
	v_exp_f32_e32 v90, v90
	v_exp_f32_e32 v91, v91
	v_exp_f32_e32 v92, v92
	v_exp_f32_e32 v93, v93
	v_exp_f32_e32 v94, v94
	v_add_f32_e32 v82, 1.0, v82
	v_add_f32_e32 v83, 1.0, v83
	v_add_f32_e32 v85, 1.0, v85
	v_add_f32_e32 v95, 1.0, v90
	v_add_f32_e32 v96, 1.0, v91
	v_add_f32_e32 v97, 1.0, v92
	v_add_f32_e32 v98, 1.0, v93
	v_add_f32_e32 v99, 1.0, v94
	v_rcp_f32_e32 v82, v82
	v_rcp_f32_e32 v83, v83
	v_rcp_f32_e32 v90, v85
	v_rcp_f32_e32 v91, v95
	v_rcp_f32_e32 v92, v96
	v_rcp_f32_e32 v93, v97
	v_rcp_f32_e32 v94, v98
	v_rcp_f32_e32 v95, v99
	v_pk_mul_f32 v[78:79], v[78:79], v[82:83]
	v_pk_mul_f32 v[80:81], v[80:81], v[90:91]
	v_pk_mul_f32 v[74:75], v[74:75], v[92:93]
	v_pk_mul_f32 v[76:77], v[76:77], v[94:95]
	v_pk_mul_f32 v[70:71], v[70:71], v[78:79]
	v_pk_mul_f32 v[72:73], v[72:73], v[80:81]
	v_pk_mul_f32 v[74:75], v[66:67], v[74:75]
	v_pk_mul_f32 v[76:77], v[68:69], v[76:77]
	v_cvt_pk_bf16_f32 v66, v70, v71
	v_cvt_pk_bf16_f32 v67, v72, v73
	v_cvt_pk_bf16_f32 v68, v74, v75
	v_cvt_pk_bf16_f32 v69, v76, v77
	global_store_dwordx4 v[86:87], v[66:69], off
	s_waitcnt vmcnt(7)
	s_nop 1
	v_mov_b32_e32 v66, v187
	v_mad_i64_i32 v[70:71], s[62:63], v84, s60, v[146:147]
	v_add_u32_e32 v68, 0x90, v150
	v_ashrrev_i32_e32 v69, 31, v68
	v_lshl_add_u64 v[72:73], v[68:69], 2, s[8:9]
	v_lshl_add_u64 v[70:71], v[70:71], 0, v[148:149]
	v_pk_mul_f32 v[64:65], v[64:65], v[66:67] op_sel_hi:[1,0]
	v_pk_mul_f32 v[62:63], v[62:63], v[66:67] op_sel_hi:[1,0]
	v_pk_mul_f32 v[60:61], v[60:61], v[66:67] op_sel_hi:[1,0]
	v_pk_mul_f32 v[58:59], v[58:59], v[66:67] op_sel_hi:[1,0]
	v_pk_mul_f32 v[56:57], v[56:57], v[66:67] op_sel_hi:[1,0]
	v_pk_mul_f32 v[54:55], v[54:55], v[66:67] op_sel_hi:[1,0]
	v_pk_mul_f32 v[52:53], v[52:53], v[66:67] op_sel_hi:[1,0]
	v_pk_mul_f32 v[50:51], v[50:51], v[66:67] op_sel_hi:[1,0]
	v_mul_f32_e32 v66, 0xbfb8aa3b, v62
	v_mul_f32_e32 v67, 0xbfb8aa3b, v63
	v_mul_f32_e32 v69, 0xbfb8aa3b, v64
	v_mul_f32_e32 v74, 0xbfb8aa3b, v65
	v_mul_f32_e32 v75, 0xbfb8aa3b, v58
	v_mul_f32_e32 v76, 0xbfb8aa3b, v59
	v_mul_f32_e32 v77, 0xbfb8aa3b, v60
	v_mul_f32_e32 v78, 0xbfb8aa3b, v61
	v_exp_f32_e32 v66, v66
	v_exp_f32_e32 v67, v67
	v_exp_f32_e32 v69, v69
	v_exp_f32_e32 v74, v74
	v_exp_f32_e32 v75, v75
	v_exp_f32_e32 v76, v76
	v_exp_f32_e32 v77, v77
	v_exp_f32_e32 v78, v78
	v_add_f32_e32 v66, 1.0, v66
	v_add_f32_e32 v67, 1.0, v67
	v_add_f32_e32 v69, 1.0, v69
	v_add_f32_e32 v79, 1.0, v74
	v_add_f32_e32 v80, 1.0, v75
	v_add_f32_e32 v81, 1.0, v76
	v_add_f32_e32 v82, 1.0, v77
	v_add_f32_e32 v83, 1.0, v78
	v_rcp_f32_e32 v66, v66
	v_rcp_f32_e32 v67, v67
	v_rcp_f32_e32 v74, v69
	v_rcp_f32_e32 v75, v79
	v_rcp_f32_e32 v76, v80
	v_rcp_f32_e32 v77, v81
	v_rcp_f32_e32 v78, v82
	v_rcp_f32_e32 v79, v83
	v_pk_mul_f32 v[62:63], v[62:63], v[66:67]
	v_pk_mul_f32 v[64:65], v[64:65], v[74:75]
	v_pk_mul_f32 v[58:59], v[58:59], v[76:77]
	v_pk_mul_f32 v[60:61], v[60:61], v[78:79]
	v_pk_mul_f32 v[54:55], v[54:55], v[62:63]
	v_pk_mul_f32 v[56:57], v[56:57], v[64:65]
	v_pk_mul_f32 v[58:59], v[50:51], v[58:59]
	v_pk_mul_f32 v[60:61], v[52:53], v[60:61]
	v_cvt_pk_bf16_f32 v50, v54, v55
	v_cvt_pk_bf16_f32 v51, v56, v57
	v_cvt_pk_bf16_f32 v52, v58, v59
	v_cvt_pk_bf16_f32 v53, v60, v61
	global_store_dwordx4 v[70:71], v[50:53], off
	s_waitcnt vmcnt(7)
	s_nop 1
	v_mov_b32_e32 v50, v188
	v_mad_i64_i32 v[54:55], s[62:63], v68, s60, v[146:147]
	v_add_u32_e32 v52, 0xa0, v150
	v_ashrrev_i32_e32 v53, 31, v52
	v_lshl_add_u64 v[56:57], v[52:53], 2, s[8:9]
	v_lshl_add_u64 v[54:55], v[54:55], 0, v[148:149]
	v_pk_mul_f32 v[48:49], v[48:49], v[50:51] op_sel_hi:[1,0]
	v_pk_mul_f32 v[46:47], v[46:47], v[50:51] op_sel_hi:[1,0]
	v_pk_mul_f32 v[44:45], v[44:45], v[50:51] op_sel_hi:[1,0]
	v_pk_mul_f32 v[42:43], v[42:43], v[50:51] op_sel_hi:[1,0]
	v_pk_mul_f32 v[40:41], v[40:41], v[50:51] op_sel_hi:[1,0]
	v_pk_mul_f32 v[38:39], v[38:39], v[50:51] op_sel_hi:[1,0]
	v_pk_mul_f32 v[36:37], v[36:37], v[50:51] op_sel_hi:[1,0]
	v_pk_mul_f32 v[34:35], v[34:35], v[50:51] op_sel_hi:[1,0]
	v_mul_f32_e32 v50, 0xbfb8aa3b, v46
	v_mul_f32_e32 v51, 0xbfb8aa3b, v47
	v_mul_f32_e32 v53, 0xbfb8aa3b, v48
	v_mul_f32_e32 v58, 0xbfb8aa3b, v49
	v_mul_f32_e32 v59, 0xbfb8aa3b, v42
	v_mul_f32_e32 v60, 0xbfb8aa3b, v43
	v_mul_f32_e32 v61, 0xbfb8aa3b, v44
	v_mul_f32_e32 v62, 0xbfb8aa3b, v45
	v_exp_f32_e32 v50, v50
	v_exp_f32_e32 v51, v51
	v_exp_f32_e32 v53, v53
	v_exp_f32_e32 v58, v58
	v_exp_f32_e32 v59, v59
	v_exp_f32_e32 v60, v60
	v_exp_f32_e32 v61, v61
	v_exp_f32_e32 v62, v62
	v_add_f32_e32 v50, 1.0, v50
	v_add_f32_e32 v51, 1.0, v51
	v_add_f32_e32 v53, 1.0, v53
	v_add_f32_e32 v63, 1.0, v58
	v_add_f32_e32 v64, 1.0, v59
	v_add_f32_e32 v65, 1.0, v60
	v_add_f32_e32 v66, 1.0, v61
	v_add_f32_e32 v67, 1.0, v62
	v_rcp_f32_e32 v50, v50
	v_rcp_f32_e32 v51, v51
	v_rcp_f32_e32 v58, v53
	v_rcp_f32_e32 v59, v63
	v_rcp_f32_e32 v60, v64
	v_rcp_f32_e32 v61, v65
	v_rcp_f32_e32 v62, v66
	v_rcp_f32_e32 v63, v67
	v_pk_mul_f32 v[46:47], v[46:47], v[50:51]
	v_pk_mul_f32 v[48:49], v[48:49], v[58:59]
	v_pk_mul_f32 v[42:43], v[42:43], v[60:61]
	v_pk_mul_f32 v[44:45], v[44:45], v[62:63]
	v_pk_mul_f32 v[38:39], v[38:39], v[46:47]
	v_pk_mul_f32 v[40:41], v[40:41], v[48:49]
	v_pk_mul_f32 v[42:43], v[34:35], v[42:43]
	v_pk_mul_f32 v[44:45], v[36:37], v[44:45]
	v_cvt_pk_bf16_f32 v34, v38, v39
	v_cvt_pk_bf16_f32 v35, v40, v41
	v_cvt_pk_bf16_f32 v36, v42, v43
	v_cvt_pk_bf16_f32 v37, v44, v45
	global_store_dwordx4 v[54:55], v[34:37], off
	s_waitcnt vmcnt(7)
	s_nop 1
	v_mov_b32_e32 v34, v189
	v_mad_i64_i32 v[38:39], s[62:63], v52, s60, v[146:147]
	v_add_u32_e32 v36, 0xb0, v150
	v_ashrrev_i32_e32 v37, 31, v36
	v_lshl_add_u64 v[40:41], v[36:37], 2, s[8:9]
	v_lshl_add_u64 v[38:39], v[38:39], 0, v[148:149]
	v_pk_mul_f32 v[32:33], v[32:33], v[34:35] op_sel_hi:[1,0]
	v_pk_mul_f32 v[30:31], v[30:31], v[34:35] op_sel_hi:[1,0]
	v_pk_mul_f32 v[28:29], v[28:29], v[34:35] op_sel_hi:[1,0]
	v_pk_mul_f32 v[26:27], v[26:27], v[34:35] op_sel_hi:[1,0]
	v_pk_mul_f32 v[24:25], v[24:25], v[34:35] op_sel_hi:[1,0]
	v_pk_mul_f32 v[22:23], v[22:23], v[34:35] op_sel_hi:[1,0]
	v_pk_mul_f32 v[20:21], v[20:21], v[34:35] op_sel_hi:[1,0]
	v_pk_mul_f32 v[18:19], v[18:19], v[34:35] op_sel_hi:[1,0]
	v_mul_f32_e32 v34, 0xbfb8aa3b, v30
	v_mul_f32_e32 v35, 0xbfb8aa3b, v31
	v_mul_f32_e32 v37, 0xbfb8aa3b, v32
	v_mul_f32_e32 v42, 0xbfb8aa3b, v33
	v_mul_f32_e32 v43, 0xbfb8aa3b, v26
	v_mul_f32_e32 v44, 0xbfb8aa3b, v27
	v_mul_f32_e32 v45, 0xbfb8aa3b, v28
	v_mul_f32_e32 v46, 0xbfb8aa3b, v29
	v_exp_f32_e32 v34, v34
	v_exp_f32_e32 v35, v35
	v_exp_f32_e32 v37, v37
	v_exp_f32_e32 v42, v42
	v_exp_f32_e32 v43, v43
	v_exp_f32_e32 v44, v44
	v_exp_f32_e32 v45, v45
	v_exp_f32_e32 v46, v46
	v_add_f32_e32 v34, 1.0, v34
	v_add_f32_e32 v35, 1.0, v35
	v_add_f32_e32 v37, 1.0, v37
	v_add_f32_e32 v47, 1.0, v42
	v_add_f32_e32 v48, 1.0, v43
	v_add_f32_e32 v49, 1.0, v44
	v_add_f32_e32 v50, 1.0, v45
	v_add_f32_e32 v51, 1.0, v46
	v_rcp_f32_e32 v34, v34
	v_rcp_f32_e32 v35, v35
	v_rcp_f32_e32 v42, v37
	v_rcp_f32_e32 v43, v47
	v_rcp_f32_e32 v44, v48
	v_rcp_f32_e32 v45, v49
	v_rcp_f32_e32 v46, v50
	v_rcp_f32_e32 v47, v51
	v_pk_mul_f32 v[30:31], v[30:31], v[34:35]
	v_pk_mul_f32 v[32:33], v[32:33], v[42:43]
	v_pk_mul_f32 v[26:27], v[26:27], v[44:45]
	v_pk_mul_f32 v[28:29], v[28:29], v[46:47]
	v_pk_mul_f32 v[22:23], v[22:23], v[30:31]
	v_pk_mul_f32 v[24:25], v[24:25], v[32:33]
	v_pk_mul_f32 v[26:27], v[18:19], v[26:27]
	v_pk_mul_f32 v[28:29], v[20:21], v[28:29]
	v_cvt_pk_bf16_f32 v18, v22, v23
	v_cvt_pk_bf16_f32 v19, v24, v25
	v_cvt_pk_bf16_f32 v20, v26, v27
	v_cvt_pk_bf16_f32 v21, v28, v29
	global_store_dwordx4 v[38:39], v[18:21], off
	s_waitcnt vmcnt(7)
	s_nop 1
	v_mov_b32_e32 v18, v190
	v_pk_mul_f32 v[16:17], v[16:17], v[18:19] op_sel_hi:[1,0]
	v_pk_mul_f32 v[14:15], v[14:15], v[18:19] op_sel_hi:[1,0]
	v_pk_mul_f32 v[12:13], v[12:13], v[18:19] op_sel_hi:[1,0]
	v_pk_mul_f32 v[10:11], v[10:11], v[18:19] op_sel_hi:[1,0]
	v_pk_mul_f32 v[8:9], v[8:9], v[18:19] op_sel_hi:[1,0]
	v_pk_mul_f32 v[6:7], v[6:7], v[18:19] op_sel_hi:[1,0]
	v_pk_mul_f32 v[4:5], v[4:5], v[18:19] op_sel_hi:[1,0]
	v_pk_mul_f32 v[2:3], v[2:3], v[18:19] op_sel_hi:[1,0]
	v_mul_f32_e32 v18, 0xbfb8aa3b, v14
	v_mul_f32_e32 v19, 0xbfb8aa3b, v15
	v_mul_f32_e32 v22, 0xbfb8aa3b, v16
	v_mul_f32_e32 v23, 0xbfb8aa3b, v17
	v_mul_f32_e32 v24, 0xbfb8aa3b, v10
	v_mul_f32_e32 v25, 0xbfb8aa3b, v11
	v_mul_f32_e32 v26, 0xbfb8aa3b, v12
	v_mul_f32_e32 v27, 0xbfb8aa3b, v13
	v_exp_f32_e32 v18, v18
	v_exp_f32_e32 v19, v19
	v_exp_f32_e32 v22, v22
	v_exp_f32_e32 v23, v23
	v_exp_f32_e32 v24, v24
	v_exp_f32_e32 v25, v25
	v_exp_f32_e32 v26, v26
	v_exp_f32_e32 v27, v27
	v_add_f32_e32 v18, 1.0, v18
	v_add_f32_e32 v19, 1.0, v19
	v_add_f32_e32 v22, 1.0, v22
	v_add_f32_e32 v23, 1.0, v23
	v_add_f32_e32 v24, 1.0, v24
	v_add_f32_e32 v25, 1.0, v25
	v_add_f32_e32 v26, 1.0, v26
	v_add_f32_e32 v27, 1.0, v27
	v_rcp_f32_e32 v18, v18
	v_rcp_f32_e32 v19, v19
	v_rcp_f32_e32 v22, v22
	v_rcp_f32_e32 v23, v23
	v_rcp_f32_e32 v24, v24
	v_rcp_f32_e32 v25, v25
	v_rcp_f32_e32 v26, v26
	v_rcp_f32_e32 v27, v27
	v_pk_mul_f32 v[14:15], v[14:15], v[18:19]
	v_pk_mul_f32 v[16:17], v[16:17], v[22:23]
	v_pk_mul_f32 v[10:11], v[10:11], v[24:25]
	v_pk_mul_f32 v[12:13], v[12:13], v[26:27]
	v_mad_i64_i32 v[20:21], s[62:63], v36, s60, v[146:147]
	v_pk_mul_f32 v[6:7], v[6:7], v[14:15]
	v_pk_mul_f32 v[8:9], v[8:9], v[16:17]
	v_pk_mul_f32 v[10:11], v[2:3], v[10:11]
	v_pk_mul_f32 v[12:13], v[4:5], v[12:13]
	v_lshl_add_u64 v[20:21], v[20:21], 0, v[148:149]
	v_cvt_pk_bf16_f32 v2, v6, v7
	v_cvt_pk_bf16_f32 v3, v8, v9
	v_cvt_pk_bf16_f32 v4, v10, v11
	v_cvt_pk_bf16_f32 v5, v12, v13
	global_store_dwordx4 v[20:21], v[2:5], off
	s_cbranch_vccnz .LBB0_825
	s_andn2_b64 vcc, exec, s[6:7]
	s_cbranch_vccnz .LBB0_824
	s_barrier
	s_branch .LBB0_824
